# HM filler loads without the nt hint
# baseline (speedup 1.0000x reference)
; __device__ __forceinline__ void st_wt16(void* p, u32x4 v) { asm volatile("global_store_dwordx4 %0, %1, off sc1\n\ts_nop 1" : : "v"(p), "v"(v) : "memory"); }
; __device__ __forceinline__ void p5_fixup(const Params& p) {
;     ...
;     for (int v0 = gtid; v0 < T_TOK * 128; v0 += 4 * gsz) {
;         u32x4 hv[4]; float4 s0[4], s1[4];
; #pragma unroll
;         for (int u = 0; u < 4; ++u) { const int v = v0 + u * gsz; if (v < T_TOK * 128) { const int row = v >> 7, head = (v >> 5) & 3;
;             hv[u] = __builtin_nontemporal_load((const u32x4*)(HM + (size_t)v * 8)); s0[u] = *(const float4*)(SSQ + ((size_t)row * 4 + head) * 8); s1[u] = *(const float4*)(SSQ + ((size_t)row * 4 + head) * 8 + 4); } }
; #pragma unroll
;         for (int u = 0; u < 4; ++u) { const int v = v0 + u * gsz; if (v < T_TOK * 128) {
;             const float ss = (s0[u].x + s0[u].y) + (s0[u].z + s0[u].w) + (s1[u].x + s1[u].y) + (s1[u].z + s1[u].w);
;             const float rstd = rsqrtf(ss * (1.0f / 256.0f) + EPS);
;             float f[8]; unpack8(hv[u], f);
; #pragma unroll
;             for (int e = 0; e < 8; ++e) f[e] *= rstd;
;             st_wt16(HM + (size_t)v * 8, pack8(f)); } }
.Lattn_perm_done:
	s_mov_b32 s99, 0
	s_cmp_lt_i32 s90, 6
	s_cselect_b64 s[0:1], -1, 0
	s_and_b64 s[96:97], s[0:1], s[2:3]
	s_andn2_b64 vcc, exec, s[96:97]
	s_cbranch_vccnz .LBB0_629
	s_cmp_eq_u32 s82, 0x100
	s_cbranch_scc0 .Lf4_done
	v_readlane_b32 s96, v254, 23
	v_readlane_b32 s97, v254, 24
	v_lshlrev_b32_e32 v64, 4, v212
	v_mov_b32_e32 v65, s84
	v_lshl_add_u32 v64, v65, 15, v64
	v_lshlrev_b32_e32 v65, 11, v65
	v_and_b32_e32 v60, 0x1e0, v212
	v_add_u32_e32 v65, v65, v60
	v_and_b32_e32 v60, 7, v212
	v_lshl_add_u32 v65, v60, 2, v65
	v_add_u32_e32 v65, 0xfd80000, v65
	s_nop 4
	v_mov_b32_e32 v62, v64
	global_load_dwordx4 v[20:23], v62, s[96:97]
	v_add_u32_e32 v62, 0x2000, v64
	global_load_dwordx4 v[24:27], v62, s[96:97]
	v_add_u32_e32 v62, 0x4000, v64
	global_load_dwordx4 v[28:31], v62, s[96:97]
	v_add_u32_e32 v62, 0x6000, v64
	global_load_dwordx4 v[32:35], v62, s[96:97]
	v_add_u32_e32 v62, 0x800000, v64
	global_load_dwordx4 v[36:39], v62, s[96:97]
	v_add_u32_e32 v62, 0x802000, v64
	global_load_dwordx4 v[40:43], v62, s[96:97]
	v_add_u32_e32 v62, 0x804000, v64
	global_load_dwordx4 v[44:47], v62, s[96:97]
	v_add_u32_e32 v62, 0x806000, v64
	global_load_dwordx4 v[48:51], v62, s[96:97]
	v_mov_b32_e32 v62, v65
	global_load_dword v52, v62, s[88:89]
	v_add_u32_e32 v62, 0x200, v65
	global_load_dword v53, v62, s[88:89]
	v_add_u32_e32 v62, 0x400, v65
	global_load_dword v54, v62, s[88:89]
	v_add_u32_e32 v62, 0x600, v65
	global_load_dword v55, v62, s[88:89]
	v_add_u32_e32 v62, 0x80000, v65
	global_load_dword v56, v62, s[88:89]
	v_add_u32_e32 v62, 0x80200, v65
	global_load_dword v57, v62, s[88:89]
	v_add_u32_e32 v62, 0x80400, v65
	global_load_dword v58, v62, s[88:89]
	v_add_u32_e32 v62, 0x80600, v65
	global_load_dword v59, v62, s[88:89]
	s_waitcnt vmcnt(0)
	v_add_f32_dpp v52, v52, v52 quad_perm:[1,0,3,2] row_mask:0xf bank_mask:0xf
	v_add_f32_dpp v53, v53, v53 quad_perm:[1,0,3,2] row_mask:0xf bank_mask:0xf
	v_add_f32_dpp v54, v54, v54 quad_perm:[1,0,3,2] row_mask:0xf bank_mask:0xf
	v_add_f32_dpp v55, v55, v55 quad_perm:[1,0,3,2] row_mask:0xf bank_mask:0xf
	v_add_f32_dpp v56, v56, v56 quad_perm:[1,0,3,2] row_mask:0xf bank_mask:0xf
	v_add_f32_dpp v57, v57, v57 quad_perm:[1,0,3,2] row_mask:0xf bank_mask:0xf
	v_add_f32_dpp v58, v58, v58 quad_perm:[1,0,3,2] row_mask:0xf bank_mask:0xf
	v_add_f32_dpp v59, v59, v59 quad_perm:[1,0,3,2] row_mask:0xf bank_mask:0xf
	v_add_f32_dpp v52, v52, v52 quad_perm:[2,3,0,1] row_mask:0xf bank_mask:0xf
	v_add_f32_dpp v53, v53, v53 quad_perm:[2,3,0,1] row_mask:0xf bank_mask:0xf
	v_add_f32_dpp v54, v54, v54 quad_perm:[2,3,0,1] row_mask:0xf bank_mask:0xf
	v_add_f32_dpp v55, v55, v55 quad_perm:[2,3,0,1] row_mask:0xf bank_mask:0xf
	v_add_f32_dpp v56, v56, v56 quad_perm:[2,3,0,1] row_mask:0xf bank_mask:0xf
	v_add_f32_dpp v57, v57, v57 quad_perm:[2,3,0,1] row_mask:0xf bank_mask:0xf
	v_add_f32_dpp v58, v58, v58 quad_perm:[2,3,0,1] row_mask:0xf bank_mask:0xf
	v_add_f32_dpp v59, v59, v59 quad_perm:[2,3,0,1] row_mask:0xf bank_mask:0xf
	v_add_f32_dpp v52, v52, v52 row_half_mirror row_mask:0xf bank_mask:0xf
	v_add_f32_dpp v53, v53, v53 row_half_mirror row_mask:0xf bank_mask:0xf
	v_add_f32_dpp v54, v54, v54 row_half_mirror row_mask:0xf bank_mask:0xf
	v_add_f32_dpp v55, v55, v55 row_half_mirror row_mask:0xf bank_mask:0xf
	v_add_f32_dpp v56, v56, v56 row_half_mirror row_mask:0xf bank_mask:0xf
	v_add_f32_dpp v57, v57, v57 row_half_mirror row_mask:0xf bank_mask:0xf
	v_add_f32_dpp v58, v58, v58 row_half_mirror row_mask:0xf bank_mask:0xf
	v_add_f32_dpp v59, v59, v59 row_half_mirror row_mask:0xf bank_mask:0xf
	v_mov_b32_e32 v60, 0x358637bd
	v_fmamk_f32 v52, v52, 0x3b800000, v60
	v_fmamk_f32 v53, v53, 0x3b800000, v60
	v_fmamk_f32 v54, v54, 0x3b800000, v60
	v_fmamk_f32 v55, v55, 0x3b800000, v60
	v_fmamk_f32 v56, v56, 0x3b800000, v60
	v_fmamk_f32 v57, v57, 0x3b800000, v60
	v_fmamk_f32 v58, v58, 0x3b800000, v60
	v_fmamk_f32 v59, v59, 0x3b800000, v60
	v_rsq_f32_e32 v52, v52
	v_rsq_f32_e32 v53, v53
	v_rsq_f32_e32 v54, v54
	v_rsq_f32_e32 v55, v55
	v_rsq_f32_e32 v56, v56
	v_rsq_f32_e32 v57, v57
	v_rsq_f32_e32 v58, v58
	v_rsq_f32_e32 v59, v59
	s_nop 0
	v_lshlrev_b32_e32 v62, 16, v20
	v_and_b32_e32 v63, 0xffff0000, v20
	v_mul_f32_e32 v62, v52, v62
	v_mul_f32_e32 v63, v52, v63
	v_cvt_pk_bf16_f32 v20, v62, v63
	v_lshlrev_b32_e32 v62, 16, v21
	v_and_b32_e32 v63, 0xffff0000, v21
	v_mul_f32_e32 v62, v52, v62
	v_mul_f32_e32 v63, v52, v63
	v_cvt_pk_bf16_f32 v21, v62, v63
	v_lshlrev_b32_e32 v62, 16, v22
	v_and_b32_e32 v63, 0xffff0000, v22
	v_mul_f32_e32 v62, v52, v62
	v_mul_f32_e32 v63, v52, v63
	v_cvt_pk_bf16_f32 v22, v62, v63
	v_lshlrev_b32_e32 v62, 16, v23
	v_and_b32_e32 v63, 0xffff0000, v23
	v_mul_f32_e32 v62, v52, v62
	v_mul_f32_e32 v63, v52, v63
	v_cvt_pk_bf16_f32 v23, v62, v63
	v_mov_b32_e32 v62, v64
	global_store_dwordx4 v62, v[20:23], s[96:97] sc1
	v_lshlrev_b32_e32 v62, 16, v24
	v_and_b32_e32 v63, 0xffff0000, v24
	v_mul_f32_e32 v62, v53, v62
	v_mul_f32_e32 v63, v53, v63
; __device__ __forceinline__ void st_wt16(void* p, u32x4 v) { asm volatile("global_store_dwordx4 %0, %1, off sc1\n\ts_nop 1" : : "v"(p), "v"(v) : "memory"); }
; __device__ __forceinline__ void p5_fixup(const Params& p) {
;     ...
;         for (int u = 0; u < 4; ++u) { const int v = v0 + u * gsz; if (v < T_TOK * 128) {
;             const float ss = (s0[u].x + s0[u].y) + (s0[u].z + s0[u].w) + (s1[u].x + s1[u].y) + (s1[u].z + s1[u].w);
;             const float rstd = rsqrtf(ss * (1.0f / 256.0f) + EPS);
;             float f[8]; unpack8(hv[u], f);
; #pragma unroll
;             for (int e = 0; e < 8; ++e) f[e] *= rstd;
;             st_wt16(HM + (size_t)v * 8, pack8(f)); } }
	v_cvt_pk_bf16_f32 v24, v62, v63
	v_lshlrev_b32_e32 v62, 16, v25
	v_and_b32_e32 v63, 0xffff0000, v25
	v_mul_f32_e32 v62, v53, v62
	v_mul_f32_e32 v63, v53, v63
	v_cvt_pk_bf16_f32 v25, v62, v63
	v_lshlrev_b32_e32 v62, 16, v26
	v_and_b32_e32 v63, 0xffff0000, v26
	v_mul_f32_e32 v62, v53, v62
	v_mul_f32_e32 v63, v53, v63
	v_cvt_pk_bf16_f32 v26, v62, v63
	v_lshlrev_b32_e32 v62, 16, v27
	v_and_b32_e32 v63, 0xffff0000, v27
	v_mul_f32_e32 v62, v53, v62
	v_mul_f32_e32 v63, v53, v63
	v_cvt_pk_bf16_f32 v27, v62, v63
	v_add_u32_e32 v62, 0x2000, v64
	global_store_dwordx4 v62, v[24:27], s[96:97] sc1
	v_lshlrev_b32_e32 v62, 16, v28
	v_and_b32_e32 v63, 0xffff0000, v28
	v_mul_f32_e32 v62, v54, v62
	v_mul_f32_e32 v63, v54, v63
	v_cvt_pk_bf16_f32 v28, v62, v63
	v_lshlrev_b32_e32 v62, 16, v29
	v_and_b32_e32 v63, 0xffff0000, v29
	v_mul_f32_e32 v62, v54, v62
	v_mul_f32_e32 v63, v54, v63
	v_cvt_pk_bf16_f32 v29, v62, v63
	v_lshlrev_b32_e32 v62, 16, v30
	v_and_b32_e32 v63, 0xffff0000, v30
	v_mul_f32_e32 v62, v54, v62
	v_mul_f32_e32 v63, v54, v63
	v_cvt_pk_bf16_f32 v30, v62, v63
	v_lshlrev_b32_e32 v62, 16, v31
	v_and_b32_e32 v63, 0xffff0000, v31
	v_mul_f32_e32 v62, v54, v62
	v_mul_f32_e32 v63, v54, v63
	v_cvt_pk_bf16_f32 v31, v62, v63
	v_add_u32_e32 v62, 0x4000, v64
	global_store_dwordx4 v62, v[28:31], s[96:97] sc1
	v_lshlrev_b32_e32 v62, 16, v32
	v_and_b32_e32 v63, 0xffff0000, v32
	v_mul_f32_e32 v62, v55, v62
	v_mul_f32_e32 v63, v55, v63
	v_cvt_pk_bf16_f32 v32, v62, v63
	v_lshlrev_b32_e32 v62, 16, v33
	v_and_b32_e32 v63, 0xffff0000, v33
	v_mul_f32_e32 v62, v55, v62
	v_mul_f32_e32 v63, v55, v63
	v_cvt_pk_bf16_f32 v33, v62, v63
	v_lshlrev_b32_e32 v62, 16, v34
	v_and_b32_e32 v63, 0xffff0000, v34
	v_mul_f32_e32 v62, v55, v62
	v_mul_f32_e32 v63, v55, v63
	v_cvt_pk_bf16_f32 v34, v62, v63
	v_lshlrev_b32_e32 v62, 16, v35
	v_and_b32_e32 v63, 0xffff0000, v35
	v_mul_f32_e32 v62, v55, v62
	v_mul_f32_e32 v63, v55, v63
	v_cvt_pk_bf16_f32 v35, v62, v63
	v_add_u32_e32 v62, 0x6000, v64
	global_store_dwordx4 v62, v[32:35], s[96:97] sc1
	v_lshlrev_b32_e32 v62, 16, v36
	v_and_b32_e32 v63, 0xffff0000, v36
	v_mul_f32_e32 v62, v56, v62
	v_mul_f32_e32 v63, v56, v63
	v_cvt_pk_bf16_f32 v36, v62, v63
	v_lshlrev_b32_e32 v62, 16, v37
	v_and_b32_e32 v63, 0xffff0000, v37
	v_mul_f32_e32 v62, v56, v62
	v_mul_f32_e32 v63, v56, v63
	v_cvt_pk_bf16_f32 v37, v62, v63
	v_lshlrev_b32_e32 v62, 16, v38
	v_and_b32_e32 v63, 0xffff0000, v38
	v_mul_f32_e32 v62, v56, v62
	v_mul_f32_e32 v63, v56, v63
	v_cvt_pk_bf16_f32 v38, v62, v63
	v_lshlrev_b32_e32 v62, 16, v39
	v_and_b32_e32 v63, 0xffff0000, v39
	v_mul_f32_e32 v62, v56, v62
	v_mul_f32_e32 v63, v56, v63
	v_cvt_pk_bf16_f32 v39, v62, v63
	v_add_u32_e32 v62, 0x800000, v64
	global_store_dwordx4 v62, v[36:39], s[96:97] sc1
	v_lshlrev_b32_e32 v62, 16, v40
	v_and_b32_e32 v63, 0xffff0000, v40
	v_mul_f32_e32 v62, v57, v62
	v_mul_f32_e32 v63, v57, v63
	v_cvt_pk_bf16_f32 v40, v62, v63
	v_lshlrev_b32_e32 v62, 16, v41
	v_and_b32_e32 v63, 0xffff0000, v41
	v_mul_f32_e32 v62, v57, v62
	v_mul_f32_e32 v63, v57, v63
	v_cvt_pk_bf16_f32 v41, v62, v63
	v_lshlrev_b32_e32 v62, 16, v42
	v_and_b32_e32 v63, 0xffff0000, v42
	v_mul_f32_e32 v62, v57, v62
	v_mul_f32_e32 v63, v57, v63
	v_cvt_pk_bf16_f32 v42, v62, v63
	v_lshlrev_b32_e32 v62, 16, v43
	v_and_b32_e32 v63, 0xffff0000, v43
	v_mul_f32_e32 v62, v57, v62
	v_mul_f32_e32 v63, v57, v63
	v_cvt_pk_bf16_f32 v43, v62, v63
	v_add_u32_e32 v62, 0x802000, v64
	global_store_dwordx4 v62, v[40:43], s[96:97] sc1
	v_lshlrev_b32_e32 v62, 16, v44
	v_and_b32_e32 v63, 0xffff0000, v44
	v_mul_f32_e32 v62, v58, v62
	v_mul_f32_e32 v63, v58, v63
	v_cvt_pk_bf16_f32 v44, v62, v63
	v_lshlrev_b32_e32 v62, 16, v45
	v_and_b32_e32 v63, 0xffff0000, v45
	v_mul_f32_e32 v62, v58, v62
	v_mul_f32_e32 v63, v58, v63
	v_cvt_pk_bf16_f32 v45, v62, v63
	v_lshlrev_b32_e32 v62, 16, v46
	v_and_b32_e32 v63, 0xffff0000, v46
	v_mul_f32_e32 v62, v58, v62
	v_mul_f32_e32 v63, v58, v63
	v_cvt_pk_bf16_f32 v46, v62, v63
	v_lshlrev_b32_e32 v62, 16, v47
	v_and_b32_e32 v63, 0xffff0000, v47
	v_mul_f32_e32 v62, v58, v62
	v_mul_f32_e32 v63, v58, v63
	v_cvt_pk_bf16_f32 v47, v62, v63
	v_add_u32_e32 v62, 0x804000, v64
	global_store_dwordx4 v62, v[44:47], s[96:97] sc1
	v_lshlrev_b32_e32 v62, 16, v48
	v_and_b32_e32 v63, 0xffff0000, v48
	v_mul_f32_e32 v62, v59, v62
	v_mul_f32_e32 v63, v59, v63
	v_cvt_pk_bf16_f32 v48, v62, v63
	v_lshlrev_b32_e32 v62, 16, v49
	v_and_b32_e32 v63, 0xffff0000, v49
	v_mul_f32_e32 v62, v59, v62
	v_mul_f32_e32 v63, v59, v63
	v_cvt_pk_bf16_f32 v49, v62, v63
	v_lshlrev_b32_e32 v62, 16, v50
	v_and_b32_e32 v63, 0xffff0000, v50
	v_mul_f32_e32 v62, v59, v62
	v_mul_f32_e32 v63, v59, v63
	v_cvt_pk_bf16_f32 v50, v62, v63
	v_lshlrev_b32_e32 v62, 16, v51
	v_and_b32_e32 v63, 0xffff0000, v51
	v_mul_f32_e32 v62, v59, v62
	v_mul_f32_e32 v63, v59, v63
	v_cvt_pk_bf16_f32 v51, v62, v63
	v_add_u32_e32 v62, 0x806000, v64
	global_store_dwordx4 v62, v[48:51], s[96:97] sc1
	s_nop 1
